# seam poll loops sleep 4 instead of 1 between polls
# baseline (speedup 1.0000x reference)
.LBB0_153:
	s_sleep 4
	global_load_dword v2, v0, s[4:5] offset:32 sc1
	s_waitcnt vmcnt(0)
	v_and_b32_e32 v2, 0xffff0000, v2
	v_cmp_ne_u32_e32 vcc, v2, v1
	s_or_b64 s[6:7], vcc, s[6:7]
	s_andn2_b64 exec, exec, s[6:7]
	s_cbranch_execnz .LBB0_153

.LBB0_161:
	s_add_u32 s8, s14, s6
	s_addc_u32 s9, s15, s7
	global_load_dword v3, v1, s[8:9] sc1
	s_waitcnt vmcnt(0)
	v_cmp_ne_u32_e32 vcc, 0, v3
	s_cmp_lg_u64 vcc, 0
	s_addc_u32 s10, s10, 0
	s_cmp_eq_u32 s13, s6
	s_cselect_b64 vcc, -1, 0
	s_add_u32 s6, s6, 0x100
	s_addc_u32 s7, s7, 0
	v_add_u32_e32 v2, v3, v2
	s_cmpk_eq_i32 s6, 0x1000
	v_cndmask_b32_e32 v0, v0, v3, vcc
	s_cbranch_scc0 .LBB0_161
	v_cmp_ne_u32_e32 vcc, s12, v2
	s_mov_b64 s[6:7], -1
	s_mov_b64 s[8:9], -1
	s_cbranch_vccz .LBB0_159
	s_add_i32 s11, s11, 1
	s_and_b32 s8, s11, 0xff
	s_cmp_eq_u32 s8, 0
	s_cselect_b64 s[8:9], -1, 0
	s_and_b64 vcc, exec, s[8:9]
	s_sleep 4
	s_cbranch_vccz .LBB0_159
	global_load_dword v2, v1, s[4:5] sc1
	s_waitcnt vmcnt(0)
	v_cmp_eq_u32_e32 vcc, 0, v2
	s_cbranch_vccz .LBB0_159
	s_cmp_gt_u32 s11, 0x40000
	s_mov_b64 s[6:7], 0
	s_cselect_b64 s[8:9], -1, 0
	s_branch .LBB0_159

.LBB0_177:
	s_and_b32 s20, s3, 0xff
	s_mov_b64 s[18:19], -1
	s_cmp_lg_u32 s20, 0
	s_mov_b64 s[22:23], -1
	s_sleep 4
	s_cbranch_scc1 .LBB0_180
	global_load_dword v2, v0, s[10:11] sc1
	s_waitcnt vmcnt(0)
	v_cmp_eq_u32_e32 vcc, 0, v2
	s_cbranch_vccnz .LBB0_182
	s_mov_b64 s[22:23], 0
	s_mov_b64 s[20:21], -1

.LBB0_194:
	s_and_b32 s18, s3, 0xff
	s_cmp_lg_u32 s18, 0
	s_mov_b64 s[20:21], -1
	s_sleep 4
	s_cbranch_scc1 .LBB0_197
	global_load_dword v1, v0, s[10:11] sc1
	s_waitcnt vmcnt(0)
	v_cmp_eq_u32_e32 vcc, 0, v1
	s_cbranch_vccnz .LBB0_199
	s_mov_b64 s[20:21], 0
	s_mov_b64 s[18:19], -1

.LBB0_322:
	s_add_u32 s6, s27, s4
	s_addc_u32 s7, s94, s5
	global_load_dword v2, v195, s[6:7] sc1
	s_waitcnt vmcnt(0)
	v_cmp_ne_u32_e32 vcc, 0, v2
	s_cmp_lg_u64 vcc, 0
	s_addc_u32 s8, s8, 0
	s_cmp_eq_u32 s9, s4
	s_cselect_b64 vcc, -1, 0
	s_add_u32 s4, s4, 0x100
	s_addc_u32 s5, s5, 0
	v_add_u32_e32 v1, v2, v1
	s_cmpk_eq_i32 s4, 0x1000
	v_cndmask_b32_e32 v0, v0, v2, vcc
	s_cbranch_scc0 .LBB0_322
	v_cmp_ne_u32_e32 vcc, s20, v1
	s_mov_b64 s[4:5], -1
	s_mov_b64 s[6:7], -1
	s_cbranch_vccz .LBB0_320
	s_add_i32 s10, s10, 1
	s_and_b32 s6, s10, 0xff
	s_cmp_eq_u32 s6, 0
	s_cselect_b64 s[6:7], -1, 0
	s_and_b64 vcc, exec, s[6:7]
	s_sleep 4
	s_cbranch_vccz .LBB0_320
	v_readlane_b32 s4, v254, 7
	v_readlane_b32 s5, v254, 8
	s_nop 4
	global_load_dword v1, v195, s[4:5] sc1
	s_mov_b64 s[4:5], -1
	s_waitcnt vmcnt(0)
	v_cmp_eq_u32_e32 vcc, 0, v1
	s_cbranch_vccz .LBB0_320
	s_cmp_gt_u32 s10, 0x40000
	s_mov_b64 s[4:5], 0
	s_cselect_b64 s[6:7], -1, 0
	s_branch .LBB0_320

.LBB0_369:
	s_and_b32 s16, s3, 0xff
	s_mov_b64 s[18:19], -1
	s_cmp_lg_u32 s16, 0
	s_mov_b64 s[24:25], -1
	s_sleep 4
	s_cbranch_scc1 .LBB0_372
	v_readlane_b32 s22, v254, 7
	v_readlane_b32 s23, v254, 8
	s_nop 4
	global_load_dword v0, v195, s[22:23] sc1
	s_waitcnt vmcnt(0)
	v_cmp_eq_u32_e32 vcc, 0, v0
	s_cbranch_vccnz .LBB0_374
	s_mov_b64 s[24:25], 0
	s_mov_b64 s[22:23], -1

.LBB0_386:
	s_and_b32 s16, s3, 0xff
	s_mov_b64 s[14:15], -1
	s_cmp_lg_u32 s16, 0
	s_mov_b64 s[22:23], -1
	s_sleep 4
	s_cbranch_scc1 .LBB0_389
	v_readlane_b32 s18, v254, 7
	v_readlane_b32 s19, v254, 8
	s_nop 4
	global_load_dword v0, v195, s[18:19] sc1
	s_waitcnt vmcnt(0)
	v_cmp_eq_u32_e32 vcc, 0, v0
	s_cbranch_vccnz .LBB0_391
	s_mov_b64 s[22:23], 0
	s_mov_b64 s[18:19], -1

.LBB0_616:
	s_add_u32 s8, s27, s4
	s_addc_u32 s9, s94, s5
	global_load_dword v2, v195, s[8:9] sc1
	s_waitcnt vmcnt(0)
	v_cmp_ne_u32_e32 vcc, 0, v2
	s_cmp_lg_u64 vcc, 0
	s_addc_u32 s6, s6, 0
	s_cmp_eq_u32 s7, s4
	s_cselect_b64 vcc, -1, 0
	s_add_u32 s4, s4, 0x100
	s_addc_u32 s5, s5, 0
	v_add_u32_e32 v1, v2, v1
	s_cmpk_eq_i32 s4, 0x1000
	v_cndmask_b32_e32 v0, v0, v2, vcc
	s_cbranch_scc0 .LBB0_616
	v_cmp_ne_u32_e32 vcc, s20, v1
	s_mov_b64 s[4:5], -1
	s_mov_b64 s[8:9], -1
	s_cbranch_vccz .LBB0_614
	s_add_i32 s10, s10, 1
	s_and_b32 s8, s10, 0xff
	s_cmp_eq_u32 s8, 0
	s_cselect_b64 s[8:9], -1, 0
	s_and_b64 vcc, exec, s[8:9]
	s_sleep 4
	s_cbranch_vccz .LBB0_614
	v_readlane_b32 s4, v254, 7
	v_readlane_b32 s5, v254, 8
	s_nop 4
	global_load_dword v1, v195, s[4:5] sc1
	s_mov_b64 s[4:5], -1
	s_waitcnt vmcnt(0)
	v_cmp_eq_u32_e32 vcc, 0, v1
	s_cbranch_vccz .LBB0_614
	s_cmp_gt_u32 s10, 0x40000
	s_mov_b64 s[4:5], 0
	s_cselect_b64 s[8:9], -1, 0
	s_branch .LBB0_614

.LBB0_632:
	s_and_b32 s6, s3, 0xff
	s_mov_b64 s[22:23], -1
	s_cmp_lg_u32 s6, 0
	s_mov_b64 s[28:29], -1
	s_sleep 4
	s_cbranch_scc1 .LBB0_635
	v_readlane_b32 s6, v254, 7
	v_readlane_b32 s7, v254, 8
	s_nop 4
	global_load_dword v0, v195, s[6:7] sc1
	s_waitcnt vmcnt(0)
	v_cmp_eq_u32_e32 vcc, 0, v0
	s_cbranch_vccnz .LBB0_637
	s_mov_b64 s[28:29], 0
	s_mov_b64 s[24:25], -1

.LBB0_649:
	s_and_b32 s6, s3, 0xff
	s_mov_b64 s[18:19], -1
	s_cmp_lg_u32 s6, 0
	s_mov_b64 s[24:25], -1
	s_sleep 4
	s_cbranch_scc1 .LBB0_652
	v_readlane_b32 s6, v254, 7
	v_readlane_b32 s7, v254, 8
	s_nop 4
	global_load_dword v0, v195, s[6:7] sc1
	s_waitcnt vmcnt(0)
	v_cmp_eq_u32_e32 vcc, 0, v0
	s_cbranch_vccnz .LBB0_654
	s_mov_b64 s[24:25], 0
	s_mov_b64 s[22:23], -1

.LBB0_734:
	s_and_b32 s6, s3, 0xff
	s_mov_b64 s[24:25], -1
	s_cmp_lg_u32 s6, 0
	s_mov_b64 s[30:31], -1
	s_sleep 4
	s_cbranch_scc1 .LBB0_737
	v_readlane_b32 s6, v254, 7
	v_readlane_b32 s7, v254, 8
	s_nop 4
	global_load_dword v0, v195, s[6:7] sc1
	s_waitcnt vmcnt(0)
	v_cmp_eq_u32_e32 vcc, 0, v0
	s_cbranch_vccnz .LBB0_739
	s_mov_b64 s[30:31], 0
	s_mov_b64 s[28:29], -1
